# v60: adaLN GEMVs of layers 1..3 deferred into the out-projection's tile-less workgroups (they finish their weight copies ~10us into a ~42us phase); prep keeps layer 0's GEMV on workgroups 0..47, copie
# speedup vs baseline: 1.0127x; 1.0109x over previous
_Z10hybrid_fwd6Params:
	s_load_dwordx16 s[64:79], s[0:1], 0x0
	s_load_dwordx16 s[4:19], s[0:1], 0x40
	s_mov_b32 s59, s2
	s_add_u32 s2, s0, 0xa8
	s_addc_u32 s3, s1, 0
	s_cmpk_lt_i32 s59, 0xc0
	s_waitcnt lgkmcnt(0)
	v_writelane_b32 v255, s4, 0
	v_and_b32_e32 v174, 0x3ff, v0
	v_and_b32_e32 v2, 63, v0
	v_writelane_b32 v255, s5, 1
	v_writelane_b32 v255, s6, 2
	v_writelane_b32 v255, s7, 3
	v_writelane_b32 v255, s8, 4
	v_writelane_b32 v255, s9, 5
	v_writelane_b32 v255, s10, 6
	v_writelane_b32 v255, s11, 7
	v_writelane_b32 v255, s12, 8
	v_writelane_b32 v255, s13, 9
	v_writelane_b32 v255, s14, 10
	v_writelane_b32 v255, s15, 11
	v_writelane_b32 v255, s16, 12
	v_writelane_b32 v255, s17, 13
	v_writelane_b32 v255, s18, 14
	v_writelane_b32 v255, s19, 15
	v_writelane_b32 v255, s2, 16
	s_cselect_b64 s[6:7], -1, 0
	s_cmpk_gt_i32 s59, 0x2f
	v_writelane_b32 v255, s3, 17
	s_load_dwordx2 s[56:57], s[0:1], 0xa0
	s_load_dword s3, s[0:1], 0xa8
	s_cselect_b64 s[8:9], -1, 0
	s_movk_i32 s2, 0x3ff
	v_bfe_u32 v6, v0, 6, 4
	s_and_b64 vcc, exec, s[8:9]
	s_cbranch_vccnz .LBB0_9
	v_lshl_add_u32 v1, v174, 2, 0
	s_mov_b64 s[4:5], 0
	s_movk_i32 s10, 0x400
	v_mov_b32_e32 v3, s77
	v_mov_b32_e32 v7, s79
	v_mov_b32_e32 v8, s76
	v_mov_b32_e32 v9, s78
	v_mov_b32_e32 v5, 0
	s_movk_i32 s11, 0x9ff
	v_mov_b32_e32 v10, v174

.LBB0_17:
	s_load_dwordx8 s[8:15], s[0:1], 0x80
	s_andn2_b64 vcc, exec, s[4:5]
	s_mov_b32 s2, s28
	s_waitcnt lgkmcnt(0)
	v_writelane_b32 v255, s8, 20
	s_nop 1
	v_writelane_b32 v255, s9, 21
	v_writelane_b32 v255, s10, 22
	v_writelane_b32 v255, s11, 23
	v_writelane_b32 v255, s12, 24
	v_writelane_b32 v255, s13, 25
	v_writelane_b32 v255, s14, 26
	v_writelane_b32 v255, s15, 27
	s_cbranch_vccnz .LBB0_19
	v_mov_b32_e32 v5, 1
	v_cmp_gt_u32_e32 vcc, 0x400, v90
	s_nop 1
	v_cndmask_b32_e64 v5, v5, 2, vcc
	v_cmp_gt_u32_e32 vcc, 0x180, v90
	s_nop 1
	v_cndmask_b32_e64 v5, v5, 0, vcc
	s_mov_b32 s2, 1

.LBB0_22:
	s_mul_i32 s8, s10, 0x480
	v_add_u32_e32 v3, s8, v90
	v_add_u32_e32 v3, 0xfffffe80, v3
	v_add_u32_e32 v8, 0x100, v90
	v_cmp_lt_u32_e32 vcc, 0x5ff, v90
	s_nop 1
	v_cndmask_b32_e32 v3, v3, v8, vcc
	v_mul_hi_i32 v8, v3, s12
	v_lshrrev_b32_e32 v13, 31, v8
	v_ashrrev_i32_e32 v8, 9, v8
	v_add_u32_e32 v18, v8, v13
	v_mul_i32_i24_e32 v8, 0x900, v18
	v_sub_u32_e32 v3, v3, v8
	v_cmp_lt_i32_e32 vcc, s13, v3
	v_ashrrev_i32_e32 v19, 31, v18
	s_and_saveexec_b64 s[8:9], vcc
	s_xor_b64 s[8:9], exec, s[8:9]
	s_cbranch_execz .LBB0_26
	v_readlane_b32 s40, v255, 0
	v_lshl_add_u32 v8, v3, 1, v27
	v_lshlrev_b32_e32 v3, 5, v3
	v_lshlrev_b64 v[16:17], 20, v[18:19]
	v_lshlrev_b64 v[18:19], 22, v[18:19]
	v_readlane_b32 s48, v255, 8
	v_readlane_b32 s49, v255, 9
	v_and_b32_e32 v21, 0x3e0, v3
	v_and_b32_e32 v15, 0x1ffc0, v8
	v_lshl_add_u64 v[18:19], s[48:49], 0, v[18:19]
	v_lshlrev_b32_e32 v8, 2, v21
	v_lshl_add_u64 v[18:19], v[18:19], 0, v[8:9]
	v_mov_b32_e32 v13, v9
	s_mov_b32 s16, 1
	v_lshl_add_u64 v[18:19], v[18:19], 0, v[12:13]
	v_or_b32_e32 v3, v1, v15
	v_or_b32_e32 v20, v6, v15
	s_mov_b32 s17, 0
	s_mov_b32 s18, 32
	v_readlane_b32 s41, v255, 1
	v_readlane_b32 s42, v255, 2
	v_readlane_b32 s43, v255, 3
	v_readlane_b32 s44, v255, 4
	v_readlane_b32 s45, v255, 5
	v_readlane_b32 s46, v255, 6
	v_readlane_b32 s47, v255, 7
	v_readlane_b32 s50, v255, 10
	v_readlane_b32 s51, v255, 11
	v_readlane_b32 s52, v255, 12
	v_readlane_b32 s53, v255, 13
	v_readlane_b32 s54, v255, 14
	v_readlane_b32 s55, v255, 15

.LBB0_30:
	s_or_b64 exec, exec, s[0:1]
	v_lshl_add_u32 v1, s59, 9, v174
	v_add_u32_e32 v1, 0xffff8000, v1
	s_mov_b32 s0, 0x10000
	s_lshl_b32 s2, s3, 9
	v_cmp_gt_u32_e32 vcc, s0, v1
	s_and_saveexec_b64 s[0:1], vcc
	s_cbranch_execz .LBB0_35
	s_add_u32 s4, s56, 0xe200000
	s_addc_u32 s5, s57, 0
	v_lshlrev_b32_e32 v3, 3, v1
	s_lshl_b32 s8, s3, 12
	s_mov_b64 s[6:7], 0
	v_mov_b32_e32 v5, 0
	s_mov_b32 s9, 0xffff
	v_mov_b32_e32 v6, v1

.LBB0_35:
	s_or_b64 exec, exec, s[0:1]
	v_lshl_add_u32 v1, s59, 9, v174
	s_mov_b32 s0, 0x20000
	v_cmp_gt_i32_e32 vcc, s0, v1
	s_and_saveexec_b64 s[0:1], vcc
	s_cbranch_execz .LBB0_40
	s_add_u32 s4, s56, 0xe400000
	s_addc_u32 s5, s57, 0
	v_lshl_add_u32 v3, s59, 12, v11
	s_lshl_b32 s8, s3, 12
	s_mov_b64 s[6:7], 0
	v_mov_b32_e32 v5, 0
	s_mov_b32 s9, 0x1ffff
	v_mov_b32_e32 v6, v1

.Ldt_done:
	s_cmp_gt_u32 s34, 2
	s_cbranch_scc1 .Lgv_skip
	s_add_i32 s20, s59, 0xffffff40
	s_cmp_gt_u32 s20, 47
	s_cbranch_scc1 .Lgv_skip
	s_add_i32 s21, s34, 1
	v_readlane_b32 s0, v255, 16
	v_readlane_b32 s1, v255, 17
	v_readfirstlane_b32 s22, v174
	s_nop 3
	s_sub_u32 s0, s0, 0xa8
	s_subb_u32 s1, s1, 0
	s_load_dwordx4 s[44:47], s[0:1], 0x30
	s_load_dwordx4 s[48:51], s[0:1], 0x48
	s_lshr_b32 s22, s22, 6
	v_and_b32_e32 v2, 63, v174
	v_lshlrev_b32_e32 v3, 2, v174
	v_add_u32_e32 v4, 0x1000, v3
	v_lshlrev_b32_e32 v5, 2, v2
	s_waitcnt lgkmcnt(0)
	global_load_dword v10, v3, s[46:47]
	global_load_dword v11, v3, s[46:47] offset:2048
	global_load_dword v12, v3, s[44:45]
	global_load_dword v13, v3, s[44:45] offset:2048
	global_load_dword v14, v4, s[44:45]
	global_load_dword v15, v4, s[44:45] offset:2048
	s_waitcnt vmcnt(0)
	v_mul_f32_e32 v20, 0xbfb8aa3b, v10
	v_exp_f32_e32 v20, v20
	s_nop 0
	v_add_f32_e32 v20, 1.0, v20
	v_div_scale_f32 v21, s[12:13], v20, v20, v10
	v_rcp_f32_e32 v22, v21
	v_div_scale_f32 v23, vcc, v10, v20, v10
	v_fma_f32 v24, -v21, v22, 1.0
	v_fmac_f32_e32 v22, v24, v22
	v_mul_f32_e32 v24, v23, v22
	v_fma_f32 v25, -v21, v24, v23
	v_fmac_f32_e32 v24, v25, v22
	v_fma_f32 v21, -v21, v24, v23
	v_div_fmas_f32 v21, v21, v22, v24
	v_div_fixup_f32 v10, v21, v20, v10
	v_mul_f32_e32 v20, 0xbfb8aa3b, v11
	v_exp_f32_e32 v20, v20
	s_nop 0
	v_add_f32_e32 v20, 1.0, v20
	v_div_scale_f32 v21, s[12:13], v20, v20, v11
	v_rcp_f32_e32 v22, v21
	v_div_scale_f32 v23, vcc, v11, v20, v11
	v_fma_f32 v24, -v21, v22, 1.0
	v_fmac_f32_e32 v22, v24, v22
	v_mul_f32_e32 v24, v23, v22
	v_fma_f32 v25, -v21, v24, v23
	v_fmac_f32_e32 v24, v25, v22
	v_fma_f32 v21, -v21, v24, v23
	v_div_fmas_f32 v21, v21, v22, v24
	v_div_fixup_f32 v11, v21, v20, v11
	v_mul_f32_e32 v20, 0xbfb8aa3b, v12
	v_exp_f32_e32 v20, v20
	s_nop 0
	v_add_f32_e32 v20, 1.0, v20
	v_div_scale_f32 v21, s[12:13], v20, v20, v12
	v_rcp_f32_e32 v22, v21
	v_div_scale_f32 v23, vcc, v12, v20, v12
	v_fma_f32 v24, -v21, v22, 1.0
	v_fmac_f32_e32 v22, v24, v22
	v_mul_f32_e32 v24, v23, v22
	v_fma_f32 v25, -v21, v24, v23
	v_fmac_f32_e32 v24, v25, v22
	v_fma_f32 v21, -v21, v24, v23
	v_div_fmas_f32 v21, v21, v22, v24
	v_div_fixup_f32 v12, v21, v20, v12
	v_mul_f32_e32 v20, 0xbfb8aa3b, v13
	v_exp_f32_e32 v20, v20
	s_nop 0
	v_add_f32_e32 v20, 1.0, v20
	v_div_scale_f32 v21, s[12:13], v20, v20, v13
	v_rcp_f32_e32 v22, v21
	v_div_scale_f32 v23, vcc, v13, v20, v13
	v_fma_f32 v24, -v21, v22, 1.0
	v_fmac_f32_e32 v22, v24, v22
	v_mul_f32_e32 v24, v23, v22
	v_fma_f32 v25, -v21, v24, v23
	v_fmac_f32_e32 v24, v25, v22
	v_fma_f32 v21, -v21, v24, v23
	v_div_fmas_f32 v21, v21, v22, v24
	v_div_fixup_f32 v13, v21, v20, v13
	v_mul_f32_e32 v20, 0xbfb8aa3b, v14
	v_exp_f32_e32 v20, v20
	s_nop 0
	v_add_f32_e32 v20, 1.0, v20
	v_div_scale_f32 v21, s[12:13], v20, v20, v14
	v_rcp_f32_e32 v22, v21
	v_div_scale_f32 v23, vcc, v14, v20, v14
	v_fma_f32 v24, -v21, v22, 1.0
	v_fmac_f32_e32 v22, v24, v22
	v_mul_f32_e32 v24, v23, v22
	v_fma_f32 v25, -v21, v24, v23
	v_fmac_f32_e32 v24, v25, v22
	v_fma_f32 v21, -v21, v24, v23
	v_div_fmas_f32 v21, v21, v22, v24
	v_div_fixup_f32 v14, v21, v20, v14
	v_mul_f32_e32 v20, 0xbfb8aa3b, v15
	v_exp_f32_e32 v20, v20
	s_nop 0
	v_add_f32_e32 v20, 1.0, v20
	v_div_scale_f32 v21, s[12:13], v20, v20, v15
	v_rcp_f32_e32 v22, v21
	v_div_scale_f32 v23, vcc, v15, v20, v15
	v_fma_f32 v24, -v21, v22, 1.0
	v_fmac_f32_e32 v22, v24, v22
	v_mul_f32_e32 v24, v23, v22
	v_fma_f32 v25, -v21, v24, v23
	v_fmac_f32_e32 v24, v25, v22
	v_fma_f32 v21, -v21, v24, v23
	v_div_fmas_f32 v21, v21, v22, v24
	v_div_fixup_f32 v15, v21, v20, v15
	ds_write_b32 v3, v10
	ds_write_b32 v3, v11 offset:2048
	ds_write_b32 v3, v12 offset:4096
	ds_write_b32 v3, v13 offset:6144
	ds_write_b32 v3, v14 offset:8192
	ds_write_b32 v3, v15 offset:10240
	s_waitcnt lgkmcnt(0)
	s_barrier
	s_mul_i32 s23, s21, 0xc00000
	s_lshl_b32 s30, s20, 8
	s_mul_i32 s36, s22, 0x180000
	s_add_u32 s48, s48, s23
	s_addc_u32 s49, s49, 0
	s_add_u32 s48, s48, s30
	s_addc_u32 s49, s49, 0
	s_add_u32 s48, s48, s36
	s_addc_u32 s49, s49, 0
	s_lshl_b32 s37, s22, 9
	v_mov_b32_e32 v6, s37
	v_mov_b32_e32 v7, 0
	v_mov_b32_e32 v8, 0
	v_mov_b32_e32 v9, 0
	s_mov_b32 s41, 4
.Lgv_b:
	global_load_dword v32, v5, s[48:49]
	s_add_u32 s48, s48, 0x3000
	s_addc_u32 s49, s49, 0
	global_load_dword v33, v5, s[48:49]
	s_add_u32 s48, s48, 0x3000
	s_addc_u32 s49, s49, 0
	global_load_dword v34, v5, s[48:49]
	s_add_u32 s48, s48, 0x3000
	s_addc_u32 s49, s49, 0
	global_load_dword v35, v5, s[48:49]
	s_add_u32 s48, s48, 0x3000
	s_addc_u32 s49, s49, 0
	global_load_dword v36, v5, s[48:49]
	s_add_u32 s48, s48, 0x3000
	s_addc_u32 s49, s49, 0
	global_load_dword v37, v5, s[48:49]
	s_add_u32 s48, s48, 0x3000
	s_addc_u32 s49, s49, 0
	global_load_dword v38, v5, s[48:49]
	s_add_u32 s48, s48, 0x3000
	s_addc_u32 s49, s49, 0
	global_load_dword v39, v5, s[48:49]
	s_add_u32 s48, s48, 0x3000
	s_addc_u32 s49, s49, 0
	global_load_dword v40, v5, s[48:49]
	s_add_u32 s48, s48, 0x3000
	s_addc_u32 s49, s49, 0
	global_load_dword v41, v5, s[48:49]
	s_add_u32 s48, s48, 0x3000
	s_addc_u32 s49, s49, 0
	global_load_dword v42, v5, s[48:49]
	s_add_u32 s48, s48, 0x3000
	s_addc_u32 s49, s49, 0
	global_load_dword v43, v5, s[48:49]
	s_add_u32 s48, s48, 0x3000
	s_addc_u32 s49, s49, 0
	global_load_dword v44, v5, s[48:49]
	s_add_u32 s48, s48, 0x3000
	s_addc_u32 s49, s49, 0
	global_load_dword v45, v5, s[48:49]
	s_add_u32 s48, s48, 0x3000
	s_addc_u32 s49, s49, 0
	global_load_dword v46, v5, s[48:49]
	s_add_u32 s48, s48, 0x3000
	s_addc_u32 s49, s49, 0
	global_load_dword v47, v5, s[48:49]
	s_add_u32 s48, s48, 0x3000
	s_addc_u32 s49, s49, 0
	global_load_dword v48, v5, s[48:49]
	s_add_u32 s48, s48, 0x3000
	s_addc_u32 s49, s49, 0
	global_load_dword v49, v5, s[48:49]
	s_add_u32 s48, s48, 0x3000
	s_addc_u32 s49, s49, 0
	global_load_dword v50, v5, s[48:49]
	s_add_u32 s48, s48, 0x3000
	s_addc_u32 s49, s49, 0
	global_load_dword v51, v5, s[48:49]
	s_add_u32 s48, s48, 0x3000
	s_addc_u32 s49, s49, 0
	global_load_dword v52, v5, s[48:49]
	s_add_u32 s48, s48, 0x3000
	s_addc_u32 s49, s49, 0
	global_load_dword v53, v5, s[48:49]
	s_add_u32 s48, s48, 0x3000
	s_addc_u32 s49, s49, 0
	global_load_dword v54, v5, s[48:49]
	s_add_u32 s48, s48, 0x3000
	s_addc_u32 s49, s49, 0
	global_load_dword v55, v5, s[48:49]
	s_add_u32 s48, s48, 0x3000
	s_addc_u32 s49, s49, 0
	global_load_dword v56, v5, s[48:49]
	s_add_u32 s48, s48, 0x3000
	s_addc_u32 s49, s49, 0
	global_load_dword v57, v5, s[48:49]
	s_add_u32 s48, s48, 0x3000
	s_addc_u32 s49, s49, 0
	global_load_dword v58, v5, s[48:49]
	s_add_u32 s48, s48, 0x3000
	s_addc_u32 s49, s49, 0
	global_load_dword v59, v5, s[48:49]
	s_add_u32 s48, s48, 0x3000
	s_addc_u32 s49, s49, 0
	global_load_dword v60, v5, s[48:49]
	s_add_u32 s48, s48, 0x3000
	s_addc_u32 s49, s49, 0
	global_load_dword v61, v5, s[48:49]
	s_add_u32 s48, s48, 0x3000
	s_addc_u32 s49, s49, 0
	global_load_dword v62, v5, s[48:49]
	s_add_u32 s48, s48, 0x3000
	s_addc_u32 s49, s49, 0
	global_load_dword v63, v5, s[48:49]
	s_add_u32 s48, s48, 0x3000
	s_addc_u32 s49, s49, 0
	ds_read_b128 v[64:67], v6
	ds_read_b128 v[68:71], v6 offset:16
	ds_read_b128 v[72:75], v6 offset:4096
	ds_read_b128 v[76:79], v6 offset:4112
	ds_read_b128 v[80:83], v6 offset:8192
	ds_read_b128 v[84:87], v6 offset:8208
	v_add_u32_e32 v6, 32, v6
	s_waitcnt lgkmcnt(0)
	s_waitcnt vmcnt(31)
	v_fmac_f32_e32 v7, v32, v64
	v_fmac_f32_e32 v8, v32, v72
	v_fmac_f32_e32 v9, v32, v80
	s_waitcnt vmcnt(30)
	v_fmac_f32_e32 v7, v33, v65
	v_fmac_f32_e32 v8, v33, v73
	v_fmac_f32_e32 v9, v33, v81
	s_waitcnt vmcnt(29)
	v_fmac_f32_e32 v7, v34, v66
	v_fmac_f32_e32 v8, v34, v74
	v_fmac_f32_e32 v9, v34, v82
	s_waitcnt vmcnt(28)
	v_fmac_f32_e32 v7, v35, v67
	v_fmac_f32_e32 v8, v35, v75
	v_fmac_f32_e32 v9, v35, v83
	s_waitcnt vmcnt(27)
	v_fmac_f32_e32 v7, v36, v68
	v_fmac_f32_e32 v8, v36, v76
	v_fmac_f32_e32 v9, v36, v84
	s_waitcnt vmcnt(26)
	v_fmac_f32_e32 v7, v37, v69
	v_fmac_f32_e32 v8, v37, v77
	v_fmac_f32_e32 v9, v37, v85
	s_waitcnt vmcnt(25)
	v_fmac_f32_e32 v7, v38, v70
	v_fmac_f32_e32 v8, v38, v78
	v_fmac_f32_e32 v9, v38, v86
	s_waitcnt vmcnt(24)
	v_fmac_f32_e32 v7, v39, v71
	v_fmac_f32_e32 v8, v39, v79
	v_fmac_f32_e32 v9, v39, v87
	ds_read_b128 v[64:67], v6
	ds_read_b128 v[68:71], v6 offset:16
	ds_read_b128 v[72:75], v6 offset:4096
	ds_read_b128 v[76:79], v6 offset:4112
	ds_read_b128 v[80:83], v6 offset:8192
	ds_read_b128 v[84:87], v6 offset:8208
	v_add_u32_e32 v6, 32, v6
	s_waitcnt lgkmcnt(0)
	s_waitcnt vmcnt(23)
	v_fmac_f32_e32 v7, v40, v64
	v_fmac_f32_e32 v8, v40, v72
	v_fmac_f32_e32 v9, v40, v80
	s_waitcnt vmcnt(22)
	v_fmac_f32_e32 v7, v41, v65
	v_fmac_f32_e32 v8, v41, v73
	v_fmac_f32_e32 v9, v41, v81
	s_waitcnt vmcnt(21)
	v_fmac_f32_e32 v7, v42, v66
	v_fmac_f32_e32 v8, v42, v74
	v_fmac_f32_e32 v9, v42, v82
	s_waitcnt vmcnt(20)
	v_fmac_f32_e32 v7, v43, v67
	v_fmac_f32_e32 v8, v43, v75
	v_fmac_f32_e32 v9, v43, v83
	s_waitcnt vmcnt(19)
	v_fmac_f32_e32 v7, v44, v68
	v_fmac_f32_e32 v8, v44, v76
	v_fmac_f32_e32 v9, v44, v84
	s_waitcnt vmcnt(18)
	v_fmac_f32_e32 v7, v45, v69
	v_fmac_f32_e32 v8, v45, v77
	v_fmac_f32_e32 v9, v45, v85
	s_waitcnt vmcnt(17)
	v_fmac_f32_e32 v7, v46, v70
	v_fmac_f32_e32 v8, v46, v78
	v_fmac_f32_e32 v9, v46, v86
	s_waitcnt vmcnt(16)
	v_fmac_f32_e32 v7, v47, v71
	v_fmac_f32_e32 v8, v47, v79
	v_fmac_f32_e32 v9, v47, v87
	ds_read_b128 v[64:67], v6
	ds_read_b128 v[68:71], v6 offset:16
	ds_read_b128 v[72:75], v6 offset:4096
	ds_read_b128 v[76:79], v6 offset:4112
	ds_read_b128 v[80:83], v6 offset:8192
	ds_read_b128 v[84:87], v6 offset:8208
	v_add_u32_e32 v6, 32, v6
	s_waitcnt lgkmcnt(0)
	s_waitcnt vmcnt(15)
	v_fmac_f32_e32 v7, v48, v64
	v_fmac_f32_e32 v8, v48, v72
	v_fmac_f32_e32 v9, v48, v80
	s_waitcnt vmcnt(14)
	v_fmac_f32_e32 v7, v49, v65
	v_fmac_f32_e32 v8, v49, v73
	v_fmac_f32_e32 v9, v49, v81
	s_waitcnt vmcnt(13)
	v_fmac_f32_e32 v7, v50, v66
	v_fmac_f32_e32 v8, v50, v74
	v_fmac_f32_e32 v9, v50, v82
	s_waitcnt vmcnt(12)
	v_fmac_f32_e32 v7, v51, v67
	v_fmac_f32_e32 v8, v51, v75
	v_fmac_f32_e32 v9, v51, v83
	s_waitcnt vmcnt(11)
	v_fmac_f32_e32 v7, v52, v68
	v_fmac_f32_e32 v8, v52, v76
	v_fmac_f32_e32 v9, v52, v84
	s_waitcnt vmcnt(10)
	v_fmac_f32_e32 v7, v53, v69
	v_fmac_f32_e32 v8, v53, v77
	v_fmac_f32_e32 v9, v53, v85
	s_waitcnt vmcnt(9)
	v_fmac_f32_e32 v7, v54, v70
	v_fmac_f32_e32 v8, v54, v78
	v_fmac_f32_e32 v9, v54, v86
	s_waitcnt vmcnt(8)
	v_fmac_f32_e32 v7, v55, v71
	v_fmac_f32_e32 v8, v55, v79
	v_fmac_f32_e32 v9, v55, v87
	ds_read_b128 v[64:67], v6
	ds_read_b128 v[68:71], v6 offset:16
	ds_read_b128 v[72:75], v6 offset:4096
	ds_read_b128 v[76:79], v6 offset:4112
	ds_read_b128 v[80:83], v6 offset:8192
	ds_read_b128 v[84:87], v6 offset:8208
	v_add_u32_e32 v6, 32, v6
	s_waitcnt lgkmcnt(0)
	s_waitcnt vmcnt(7)
	v_fmac_f32_e32 v7, v56, v64
	v_fmac_f32_e32 v8, v56, v72
	v_fmac_f32_e32 v9, v56, v80
	s_waitcnt vmcnt(6)
	v_fmac_f32_e32 v7, v57, v65
	v_fmac_f32_e32 v8, v57, v73
	v_fmac_f32_e32 v9, v57, v81
	s_waitcnt vmcnt(5)
	v_fmac_f32_e32 v7, v58, v66
	v_fmac_f32_e32 v8, v58, v74
	v_fmac_f32_e32 v9, v58, v82
	s_waitcnt vmcnt(4)
	v_fmac_f32_e32 v7, v59, v67
	v_fmac_f32_e32 v8, v59, v75
	v_fmac_f32_e32 v9, v59, v83
	s_waitcnt vmcnt(3)
	v_fmac_f32_e32 v7, v60, v68
	v_fmac_f32_e32 v8, v60, v76
	v_fmac_f32_e32 v9, v60, v84
	s_waitcnt vmcnt(2)
	v_fmac_f32_e32 v7, v61, v69
	v_fmac_f32_e32 v8, v61, v77
	v_fmac_f32_e32 v9, v61, v85
	s_waitcnt vmcnt(1)
	v_fmac_f32_e32 v7, v62, v70
	v_fmac_f32_e32 v8, v62, v78
	v_fmac_f32_e32 v9, v62, v86
	s_waitcnt vmcnt(0)
	v_fmac_f32_e32 v7, v63, v71
	v_fmac_f32_e32 v8, v63, v79
	v_fmac_f32_e32 v9, v63, v87
	s_sub_i32 s41, s41, 1
	s_cmp_lg_u32 s41, 0
	s_cbranch_scc1 .Lgv_b
	s_mul_i32 s37, s22, 0x300
	v_add_u32_e32 v16, s37, v5
	ds_write2st64_b32 v16, v7, v8 offset0:48 offset1:49
	ds_write_b32 v16, v9 offset:12800
	s_waitcnt lgkmcnt(0)
	s_barrier
	v_cmp_gt_u32_e32 vcc, 0xc0, v174
	s_and_saveexec_b64 s[0:1], vcc
	s_cbranch_execz .Lgv_fin
	s_mul_i32 s23, s21, 0x3000
	s_add_u32 s50, s50, s23
	s_addc_u32 s51, s51, 0
	s_add_u32 s50, s50, s30
	s_addc_u32 s51, s51, 0
	global_load_dword v17, v5, s[50:51]
	s_lshl_b32 s36, s22, 8
	v_add_u32_e32 v18, s36, v5
	ds_read2st64_b32 v[20:21], v18 offset0:48 offset1:51
	ds_read2st64_b32 v[22:23], v18 offset0:54 offset1:57
	ds_read2st64_b32 v[24:25], v18 offset0:60 offset1:63
	ds_read2st64_b32 v[26:27], v18 offset0:66 offset1:69
	s_mul_i32 s23, s21, 3
	s_add_i32 s23, s23, s22
	s_mul_i32 s23, s23, 0x3000
	s_add_u32 s44, s56, 0x2400000
	s_addc_u32 s45, s57, 0
	s_add_u32 s44, s44, s23
	s_addc_u32 s45, s45, 0
	s_add_u32 s44, s44, s30
	s_addc_u32 s45, s45, 0
	s_waitcnt vmcnt(0) lgkmcnt(0)
	v_add_f32_e32 v17, v17, v20
	v_add_f32_e32 v17, v17, v21
	v_add_f32_e32 v17, v17, v22
	v_add_f32_e32 v17, v17, v23
	v_add_f32_e32 v17, v17, v24
	v_add_f32_e32 v17, v17, v25
	v_add_f32_e32 v17, v17, v26
	v_add_f32_e32 v17, v17, v27
	global_store_dword v5, v17, s[44:45]
.Lgv_fin:
	s_or_b64 exec, exec, s[0:1]
.Lgv_skip:
	s_branch .LBB0_307
